# attention steady-state loops: running K/V DMA source addresses (SALU strength reduction), persistent steady loop
# speedup vs baseline: 1.0183x; 1.0021x over previous
.Lst0:
	s_mov_b32 s2, s40
	s_add_i32 s2, s2, s15
	s_sub_i32 s2, s2, 64
	s_mul_hi_i32 s3, s2, 0x600
	s_mulk_i32 s2, 0x600
	s_add_u32 s2, s12, s2
	s_addc_u32 s3, s13, s3
	s_mov_b32 s98, s2
	s_mov_b32 s99, s3
	s_mov_b32 s46, s40
	s_add_i32 s46, s46, s15
	s_addk_i32 s46, 0xff80
	s_ashr_i32 s47, s46, 31
	s_lshl_b64 s[46:47], s[46:47], 1
	s_add_u32 s46, s39, s46
	s_addc_u32 s47, s67, s47
	s_mov_b32 s100, s46
	s_mov_b32 s101, s47
.Lst0_loop:
	s_lshl_b32 s46, s41, 14
	s_add_i32 s46, s58, s46
	s_mov_b32 m0, s46
	s_nop 0
	global_load_lds_dwordx4 v198, s[98:99]
	s_add_i32 m0, s46, 0x400
	s_nop 0
	global_load_lds_dwordx4 v194, s[98:99]
	s_add_i32 s48, s20, 0xffffc000
	s_and_b32 s48, s48, 0x8000
	s_add_i32 s48, s58, s48
	s_add_i32 m0, s48, 0xc000
	s_nop 0
	global_load_lds_dwordx4 v196, s[100:101]
	s_add_i32 m0, s48, 0xc400
	s_nop 0
	global_load_lds_dwordx4 v192, s[100:101]
	s_add_i32 s46, s41, 1
	s_cmp_lg_u32 s41, 2
	s_cselect_b32 s41, s46, 0
	s_lshl_b32 s46, s41, 14
	s_add_i32 s49, s46, 0
	s_add_i32 s46, s20, 0xffff4000
	v_add_u32_e32 v100, s49, v205
	ds_read_b128 v[96:99], v100
	ds_read_b128 v[100:103], v100 offset:8192
	s_waitcnt lgkmcnt(0)
	v_mfma_f32_32x32x16_bf16 v[112:127], v[96:99], v[160:163], 0
	v_xad_u32 v104, v205, 32, s49
	ds_read_b128 v[128:131], v104
	ds_read_b128 v[132:135], v104 offset:8192
	v_xad_u32 v96, v205, 64, s49
	ds_read_b128 v[136:139], v96
	s_and_b32 s46, s46, 0x8000
	s_add_i32 s48, s46, 0
	v_exp_f32_e32 v140, v48
	v_exp_f32_e32 v141, v49
	v_exp_f32_e32 v142, v50
	v_exp_f32_e32 v143, v51
	ds_read_b128 v[48:51], v96 offset:8192
	v_mfma_f32_32x32x16_bf16 v[96:111], v[100:103], v[160:163], 0
	v_exp_f32_e32 v144, v52
	v_exp_f32_e32 v145, v53
	v_exp_f32_e32 v146, v54
	v_exp_f32_e32 v147, v55
	s_waitcnt lgkmcnt(0)
	v_mfma_f32_32x32x16_bf16 v[112:127], v[128:131], v[164:167], v[112:127]
	v_add_u32_e32 v152, s49, v213
	ds_read_b128 v[52:55], v152
	v_exp_f32_e32 v148, v56
	v_exp_f32_e32 v149, v57
	v_exp_f32_e32 v150, v58
	v_exp_f32_e32 v151, v59
	v_mfma_f32_32x32x16_bf16 v[96:111], v[132:135], v[164:167], v[96:111]
	ds_read_b128 v[56:59], v152 offset:8192
	v_exp_f32_e32 v128, v60
	v_exp_f32_e32 v129, v61
	v_exp_f32_e32 v130, v62
	v_exp_f32_e32 v131, v63
	v_mfma_f32_32x32x16_bf16 v[112:127], v[136:139], v[168:171], v[112:127]
	v_add_u32_e32 v156, s48, v206
	ds_read_b128 v[60:63], v156 offset:49152
	v_exp_f32_e32 v132, v32
	v_exp_f32_e32 v133, v33
	v_exp_f32_e32 v134, v34
	v_exp_f32_e32 v135, v35
	v_mfma_f32_32x32x16_bf16 v[96:111], v[48:51], v[168:171], v[96:111]
	ds_read_b128 v[32:35], v156 offset:53248
	v_exp_f32_e32 v136, v36
	v_exp_f32_e32 v137, v37
	v_exp_f32_e32 v138, v38
	v_exp_f32_e32 v139, v39
	s_waitcnt lgkmcnt(0)
	v_mfma_f32_32x32x16_bf16 v[112:127], v[52:55], v[172:175], v[112:127]
	ds_read_b128 v[36:39], v156 offset:57344
	v_exp_f32_e32 v152, v40
	v_exp_f32_e32 v153, v41
	v_exp_f32_e32 v154, v42
	v_exp_f32_e32 v155, v43
	v_mfma_f32_32x32x16_bf16 v[96:111], v[56:59], v[172:175], v[96:111]
	ds_read_b128 v[40:43], v156 offset:61440
	v_exp_f32_e32 v156, v44
	v_exp_f32_e32 v157, v45
	v_exp_f32_e32 v158, v46
	v_exp_f32_e32 v159, v47
	v_cvt_pk_bf16_f32 v44, v140, v141
	v_cvt_pk_bf16_f32 v45, v142, v143
	v_cvt_pk_bf16_f32 v46, v144, v145
	v_cvt_pk_bf16_f32 v47, v146, v147
	s_nop 1
	v_mfma_f32_32x32x16_bf16 v[80:95], v[60:63], v[44:47], v[80:95]
	v_xad_u32 v178, v206, 32, s48
	ds_read_b128 v[48:51], v178 offset:49152
	v_cvt_pk_bf16_f32 v52, v148, v149
	v_cvt_pk_bf16_f32 v53, v150, v151
	v_cvt_pk_bf16_f32 v54, v128, v129
	v_cvt_pk_bf16_f32 v55, v130, v131
	v_mfma_f32_32x32x16_bf16 v[64:79], v[32:35], v[44:47], v[64:79]
	ds_read_b128 v[56:59], v178 offset:53248
	v_pk_add_f32 v[62:63], v[146:147], v[142:143]
	v_pk_add_f32 v[60:61], v[144:145], v[140:141]
	s_waitcnt lgkmcnt(0)
	v_mfma_f32_32x32x16_bf16 v[16:31], v[36:39], v[44:47], v[16:31]
	ds_read_b128 v[32:35], v178 offset:57344
	v_add_f32_e64 v62, v150, v62
	v_add_f32_e64 v63, v151, v63
	v_add_f32_e64 v60, v148, v60
	v_add_f32_e64 v61, v149, v61
	v_pk_add_f32 v[62:63], v[130:131], v[62:63]
	v_pk_add_f32 v[60:61], v[128:129], v[60:61]
	v_mfma_f32_32x32x16_bf16 v[0:15], v[40:43], v[44:47], v[0:15]
	ds_read_b128 v[36:39], v178 offset:61440
	v_mfma_f32_32x32x16_bf16 v[80:95], v[48:51], v[52:55], v[80:95]
	v_xad_u32 v140, v206, 64, s48
	ds_read_b128 v[40:43], v140 offset:49152
	v_cvt_pk_bf16_f32 v44, v132, v133
	v_cvt_pk_bf16_f32 v45, v134, v135
	v_cvt_pk_bf16_f32 v46, v136, v137
	v_cvt_pk_bf16_f32 v47, v138, v139
	v_mfma_f32_32x32x16_bf16 v[64:79], v[56:59], v[52:55], v[64:79]
	ds_read_b128 v[48:51], v140 offset:53248
	v_add_f32_e64 v62, v134, v62
	v_add_f32_e64 v63, v135, v63
	v_add_f32_e64 v60, v132, v60
	v_add_f32_e64 v61, v133, v61
	v_pk_add_f32 v[62:63], v[138:139], v[62:63]
	v_pk_add_f32 v[60:61], v[136:137], v[60:61]
	s_waitcnt lgkmcnt(0)
	v_mfma_f32_32x32x16_bf16 v[16:31], v[32:35], v[52:55], v[16:31]
	ds_read_b128 v[56:59], v140 offset:57344
	v_add_f32_e64 v62, v154, v62
	v_add_f32_e64 v63, v155, v63
	v_add_f32_e64 v60, v152, v60
	v_add_f32_e64 v61, v153, v61
	v_pk_add_f32 v[130:131], v[158:159], v[62:63]
	v_pk_add_f32 v[128:129], v[156:157], v[60:61]
	v_mfma_f32_32x32x16_bf16 v[0:15], v[36:39], v[52:55], v[0:15]
	ds_read_b128 v[32:35], v140 offset:61440
	v_mfma_f32_32x32x16_bf16 v[80:95], v[40:43], v[44:47], v[80:95]
	v_add_u32_e32 v60, s48, v209
	ds_read_b128 v[36:39], v60 offset:49152
	v_cvt_pk_bf16_f32 v52, v152, v153
	v_cvt_pk_bf16_f32 v53, v154, v155
	v_cvt_pk_bf16_f32 v54, v156, v157
	v_cvt_pk_bf16_f32 v55, v158, v159
	v_mfma_f32_32x32x16_bf16 v[64:79], v[48:51], v[44:47], v[64:79]
	ds_read_b128 v[40:43], v60 offset:53248
	s_waitcnt lgkmcnt(0)
	v_mfma_f32_32x32x16_bf16 v[16:31], v[56:59], v[44:47], v[16:31]
	ds_read_b128 v[48:51], v60 offset:57344
	v_mfma_f32_32x32x16_bf16 v[0:15], v[32:35], v[44:47], v[0:15]
	ds_read_b128 v[56:59], v60 offset:61440
	v_mfma_f32_32x32x16_bf16 v[80:95], v[36:39], v[52:55], v[80:95]
	v_mfma_f32_32x32x16_bf16 v[64:79], v[40:43], v[52:55], v[64:79]
	s_waitcnt lgkmcnt(0)
	v_mfma_f32_32x32x16_bf16 v[16:31], v[48:51], v[52:55], v[16:31]
	v_mfma_f32_32x32x16_bf16 v[0:15], v[56:59], v[52:55], v[0:15]
	s_waitcnt vmcnt(4) lgkmcnt(0)
	s_barrier
	s_add_u32 s68, s98, 0x18000
	s_addc_u32 s69, s99, 0
	s_add_i32 s49, s49, s57
	s_mov_b32 m0, s49
	s_nop 0
	global_load_lds_dwordx4 v198, s[68:69]
	s_add_i32 m0, s49, 0x400
	s_nop 0
	global_load_lds_dwordx4 v194, s[68:69]
	s_add_u32 s44, s100, 0x80
	s_addc_u32 s45, s101, 0
	s_and_b32 s49, s20, 0xc000
	s_add_i32 s49, s58, s49
	s_add_i32 m0, s49, 0xc000
	s_nop 0
	global_load_lds_dwordx4 v196, s[44:45]
	s_add_i32 m0, s49, 0xc400
	s_nop 0
	global_load_lds_dwordx4 v192, s[44:45]
	s_add_i32 s48, s48, 0xc000
	s_add_i32 s44, s41, 1
	s_cmp_lg_u32 s41, 2
	s_cselect_b32 s41, s44, 0
	s_lshl_b32 s44, s41, 14
	s_add_i32 s44, s44, 0
	v_exp_f32_e32 v144, v112
	v_add_u32_e32 v36, s44, v205
	ds_read_b128 v[32:35], v36
	ds_read_b128 v[36:39], v36 offset:8192
	s_waitcnt lgkmcnt(0)
	v_mfma_f32_32x32x16_bf16 v[48:63], v[32:35], v[160:163], 0
	v_xad_u32 v40, v205, 32, s44
	ds_read_b128 v[132:135], v40
	ds_read_b128 v[136:139], v40 offset:8192
	v_xad_u32 v32, v205, 64, s44
	ds_read_b128 v[140:143], v32
	v_exp_f32_e32 v145, v113
	v_exp_f32_e32 v146, v114
	v_exp_f32_e32 v147, v115
	ds_read_b128 v[112:115], v32 offset:8192
	v_mfma_f32_32x32x16_bf16 v[32:47], v[36:39], v[160:163], 0
	v_exp_f32_e32 v148, v116
	v_exp_f32_e32 v149, v117
	v_exp_f32_e32 v150, v118
	v_exp_f32_e32 v151, v119
	s_waitcnt lgkmcnt(0)
	v_mfma_f32_32x32x16_bf16 v[48:63], v[132:135], v[164:167], v[48:63]
	v_add_u32_e32 v156, s44, v213
	ds_read_b128 v[116:119], v156
	v_exp_f32_e32 v152, v120
	v_exp_f32_e32 v153, v121
	v_exp_f32_e32 v154, v122
	v_exp_f32_e32 v155, v123
	v_mfma_f32_32x32x16_bf16 v[32:47], v[136:139], v[164:167], v[32:47]
	ds_read_b128 v[120:123], v156 offset:8192
	v_exp_f32_e32 v156, v124
	v_exp_f32_e32 v157, v125
	v_exp_f32_e32 v158, v126
	v_exp_f32_e32 v159, v127
	v_mfma_f32_32x32x16_bf16 v[48:63], v[140:143], v[168:171], v[48:63]
	v_add_u32_e32 v132, s48, v206
	ds_read_b128 v[124:127], v132 offset:16384
	v_exp_f32_e32 v136, v96
	v_exp_f32_e32 v137, v97
	v_exp_f32_e32 v138, v98
	v_exp_f32_e32 v139, v99
	v_mfma_f32_32x32x16_bf16 v[32:47], v[112:115], v[168:171], v[32:47]
	ds_read_b128 v[96:99], v132 offset:20480
	v_exp_f32_e32 v140, v100
	v_exp_f32_e32 v141, v101
	v_exp_f32_e32 v142, v102
	v_exp_f32_e32 v143, v103
	s_waitcnt lgkmcnt(0)
	v_mfma_f32_32x32x16_bf16 v[48:63], v[116:119], v[172:175], v[48:63]
	ds_read_b128 v[100:103], v132 offset:24576
	v_exp_f32_e32 v178, v104
	v_exp_f32_e32 v179, v105
	v_exp_f32_e32 v180, v106
	v_exp_f32_e32 v181, v107
	v_mfma_f32_32x32x16_bf16 v[32:47], v[120:123], v[172:175], v[32:47]
	ds_read_b128 v[104:107], v132 offset:28672
	v_exp_f32_e32 v182, v108
	v_exp_f32_e32 v183, v109
	v_exp_f32_e32 v184, v110
	v_exp_f32_e32 v185, v111
	v_cvt_pk_bf16_f32 v108, v144, v145
	v_cvt_pk_bf16_f32 v109, v146, v147
	v_cvt_pk_bf16_f32 v110, v148, v149
	v_cvt_pk_bf16_f32 v111, v150, v151
	s_nop 1
	v_mfma_f32_32x32x16_bf16 v[80:95], v[124:127], v[108:111], v[80:95]
	v_xad_u32 v186, v206, 32, s48
	ds_read_b128 v[112:115], v186 offset:16384
	v_cvt_pk_bf16_f32 v116, v152, v153
	v_cvt_pk_bf16_f32 v117, v154, v155
	v_cvt_pk_bf16_f32 v118, v156, v157
	v_cvt_pk_bf16_f32 v119, v158, v159
	v_mfma_f32_32x32x16_bf16 v[64:79], v[96:99], v[108:111], v[64:79]
	ds_read_b128 v[120:123], v186 offset:20480
	v_pk_add_f32 v[126:127], v[150:151], v[146:147]
	v_pk_add_f32 v[124:125], v[148:149], v[144:145]
	s_waitcnt lgkmcnt(0)
	v_mfma_f32_32x32x16_bf16 v[16:31], v[100:103], v[108:111], v[16:31]
	ds_read_b128 v[132:135], v186 offset:24576
	v_add_f32_e64 v98, v154, v126
	v_add_f32_e64 v99, v155, v127
	v_add_f32_e64 v96, v152, v124
	v_add_f32_e64 v97, v153, v125
	v_pk_add_f32 v[98:99], v[158:159], v[98:99]
	v_pk_add_f32 v[96:97], v[156:157], v[96:97]
	v_mfma_f32_32x32x16_bf16 v[0:15], v[104:107], v[108:111], v[0:15]
	ds_read_b128 v[100:103], v186 offset:28672
	v_mfma_f32_32x32x16_bf16 v[80:95], v[112:115], v[116:119], v[80:95]
	v_xad_u32 v124, v206, 64, s48
	ds_read_b128 v[104:107], v124 offset:16384
	v_cvt_pk_bf16_f32 v108, v136, v137
	v_cvt_pk_bf16_f32 v109, v138, v139
	v_cvt_pk_bf16_f32 v110, v140, v141
	v_cvt_pk_bf16_f32 v111, v142, v143
	v_mfma_f32_32x32x16_bf16 v[64:79], v[120:123], v[116:119], v[64:79]
	ds_read_b128 v[112:115], v124 offset:20480
	v_add_f32_e64 v98, v138, v98
	v_add_f32_e64 v99, v139, v99
	v_add_f32_e64 v96, v136, v96
	v_add_f32_e64 v97, v137, v97
	v_pk_add_f32 v[98:99], v[142:143], v[98:99]
	v_pk_add_f32 v[96:97], v[140:141], v[96:97]
	s_waitcnt lgkmcnt(0)
	v_mfma_f32_32x32x16_bf16 v[16:31], v[132:135], v[116:119], v[16:31]
	ds_read_b128 v[120:123], v124 offset:24576
	v_add_f32_e64 v98, v180, v98
	v_add_f32_e64 v99, v181, v99
	v_add_f32_e64 v96, v178, v96
	v_add_f32_e64 v97, v179, v97
	v_pk_add_f32 v[98:99], v[184:185], v[98:99]
	v_pk_add_f32 v[96:97], v[182:183], v[96:97]
	v_mfma_f32_32x32x16_bf16 v[0:15], v[100:103], v[116:119], v[0:15]
	ds_read_b128 v[124:127], v124 offset:28672
	v_mfma_f32_32x32x16_bf16 v[80:95], v[104:107], v[108:111], v[80:95]
	v_add_u32_e32 v132, s48, v209
	ds_read_b128 v[100:103], v132 offset:16384
	v_cvt_pk_bf16_f32 v116, v178, v179
	v_cvt_pk_bf16_f32 v117, v180, v181
	v_cvt_pk_bf16_f32 v118, v182, v183
	v_cvt_pk_bf16_f32 v119, v184, v185
	v_mfma_f32_32x32x16_bf16 v[64:79], v[112:115], v[108:111], v[64:79]
	ds_read_b128 v[104:107], v132 offset:20480
	s_waitcnt lgkmcnt(0)
	v_mfma_f32_32x32x16_bf16 v[16:31], v[120:123], v[108:111], v[16:31]
	ds_read_b128 v[112:115], v132 offset:24576
	v_mfma_f32_32x32x16_bf16 v[0:15], v[124:127], v[108:111], v[0:15]
	ds_read_b128 v[120:123], v132 offset:28672
	v_mfma_f32_32x32x16_bf16 v[80:95], v[100:103], v[116:119], v[80:95]
	v_mfma_f32_32x32x16_bf16 v[64:79], v[104:107], v[116:119], v[64:79]
	s_waitcnt lgkmcnt(0)
	v_mfma_f32_32x32x16_bf16 v[16:31], v[112:115], v[116:119], v[16:31]
	v_mfma_f32_32x32x16_bf16 v[0:15], v[120:123], v[116:119], v[0:15]
	s_waitcnt vmcnt(4) lgkmcnt(0)
	v_add_f32_e32 v100, v128, v129
	v_add_f32_e32 v101, v130, v131
	v_add_f32_e32 v100, v100, v101
	v_add_f32_e32 v96, v96, v97
	v_add_f32_e32 v97, v98, v99
	s_barrier
	v_add_f32_e32 v100, v177, v100
	v_add_f32_e32 v96, v96, v97
	v_add_f32_e32 v177, v100, v96
	s_add_i32 s21, s21, 2
	s_addk_i32 s15, 0x80
	s_add_i32 s20, s20, 0x8000
	s_add_u32 s98, s98, 0x30000
	s_addc_u32 s99, s99, 0
	s_add_u32 s100, s100, 0x100
	s_addc_u32 s101, s101, 0
	s_cmp_lt_u32 s21, 60
	s_cbranch_scc1 .Lst0_loop
	s_branch .LBB0_936
.Lst1:
	s_mov_b32 s44, s40
	s_add_i32 s44, s44, s41
	s_sub_i32 s44, s44, 64
	s_mul_hi_i32 s45, s44, 0x600
	s_mulk_i32 s44, 0x600
	s_add_u32 s44, s14, s44
	s_addc_u32 s45, s15, s45
	s_mov_b32 s98, s44
	s_mov_b32 s99, s45
	s_mov_b32 s44, s40
	s_add_i32 s44, s44, s41
	s_addk_i32 s44, 0xff80
	s_ashr_i32 s45, s44, 31
	s_lshl_b64 s[44:45], s[44:45], 1
	s_add_u32 s44, s39, s44
	s_addc_u32 s45, s67, s45
	s_mov_b32 s100, s44
	s_mov_b32 s101, s45
.Lst1_loop:
	s_lshl_b32 s49, s48, 14
	s_add_i32 s49, s58, s49
	s_mov_b32 m0, s49
	s_nop 0
	global_load_lds_dwordx4 v198, s[98:99]
	s_add_i32 m0, s49, 0x400
	s_nop 0
	global_load_lds_dwordx4 v194, s[98:99]
	s_add_i32 s49, s46, 0xffffc000
	s_and_b32 s49, s49, 0xc000
	s_add_i32 s49, s58, s49
	s_add_i32 m0, s49, 0xc000
	s_nop 0
	global_load_lds_dwordx4 v196, s[100:101]
	s_add_i32 m0, s49, 0xc400
	s_add_i32 s44, s48, 1
	global_load_lds_dwordx4 v192, s[100:101]
	s_cmp_lg_u32 s48, 2
	s_cselect_b32 s48, s44, 0
	s_lshl_b32 s44, s48, 14
	s_and_b32 s49, s46, 0xc000
	s_add_i32 s68, s44, 0
	s_add_i32 s44, s49, 0
	v_add_u32_e32 v156, s44, v206
	ds_read_b128 v[140:143], v156 offset:49152
	ds_read_b128 v[148:151], v156 offset:53248
	ds_read_b128 v[152:155], v156 offset:57344
	ds_read_b128 v[156:159], v156 offset:61440
	s_waitcnt lgkmcnt(0)
	v_mfma_f32_32x32x16_bf16 v[80:95], v[140:143], v[144:147], v[80:95]
	v_xad_u32 v177, v206, 32, s44
	ds_read_b128 v[140:143], v177 offset:49152
	v_mfma_f32_32x32x16_bf16 v[64:79], v[148:151], v[144:147], v[64:79]
	ds_read_b128 v[148:151], v177 offset:53248
	v_mfma_f32_32x32x16_bf16 v[16:31], v[152:155], v[144:147], v[16:31]
	ds_read_b128 v[152:155], v177 offset:57344
	v_mfma_f32_32x32x16_bf16 v[0:15], v[156:159], v[144:147], v[0:15]
	ds_read_b128 v[144:147], v177 offset:61440
	s_waitcnt lgkmcnt(0)
	v_mfma_f32_32x32x16_bf16 v[80:95], v[140:143], v[128:131], v[80:95]
	v_xad_u32 v156, v206, 64, s44
	ds_read_b128 v[140:143], v156 offset:49152
	v_mfma_f32_32x32x16_bf16 v[64:79], v[148:151], v[128:131], v[64:79]
	ds_read_b128 v[148:151], v156 offset:53248
	v_mfma_f32_32x32x16_bf16 v[16:31], v[152:155], v[128:131], v[16:31]
	ds_read_b128 v[152:155], v156 offset:57344
	v_mfma_f32_32x32x16_bf16 v[0:15], v[144:147], v[128:131], v[0:15]
	ds_read_b128 v[128:131], v156 offset:61440
	s_waitcnt lgkmcnt(0)
	v_mfma_f32_32x32x16_bf16 v[80:95], v[140:143], v[132:135], v[80:95]
	v_add_u32_e32 v156, s44, v209
	ds_read_b128 v[140:143], v156 offset:49152
	v_mfma_f32_32x32x16_bf16 v[64:79], v[148:151], v[132:135], v[64:79]
	ds_read_b128 v[144:147], v156 offset:53248
	v_mfma_f32_32x32x16_bf16 v[16:31], v[152:155], v[132:135], v[16:31]
	ds_read_b128 v[148:151], v156 offset:57344
	v_mfma_f32_32x32x16_bf16 v[0:15], v[128:131], v[132:135], v[0:15]
	ds_read_b128 v[128:131], v156 offset:61440
	s_waitcnt lgkmcnt(0)
	v_mfma_f32_32x32x16_bf16 v[80:95], v[140:143], v[136:139], v[80:95]
	v_add_u32_e32 v140, s68, v205
	ds_read_b128 v[132:135], v140
	v_mfma_f32_32x32x16_bf16 v[64:79], v[144:147], v[136:139], v[64:79]
	ds_read_b128 v[140:143], v140 offset:8192
	v_mfma_f32_32x32x16_bf16 v[16:31], v[148:151], v[136:139], v[16:31]
	v_xad_u32 v144, v205, 32, s68
	ds_read_b128 v[176:179], v144
	v_mfma_f32_32x32x16_bf16 v[0:15], v[128:131], v[136:139], v[0:15]
	ds_read_b128 v[182:185], v144 offset:8192
	s_waitcnt lgkmcnt(0)
	v_mfma_f32_32x32x16_bf16 v[144:159], v[132:135], v[160:163], 0
	v_xad_u32 v216, v205, 64, s68
	ds_read_b128 v[186:189], v216
	v_exp_f32_e32 v220, v112
	v_exp_f32_e32 v221, v113
	v_exp_f32_e32 v222, v114
	v_exp_f32_e32 v223, v115
	v_mfma_f32_32x32x16_bf16 v[128:143], v[140:143], v[160:163], 0
	ds_read_b128 v[216:219], v216 offset:8192
	v_exp_f32_e32 v224, v116
	v_exp_f32_e32 v225, v117
	v_exp_f32_e32 v226, v118
	v_exp_f32_e32 v227, v119
	v_mfma_f32_32x32x16_bf16 v[144:159], v[176:179], v[164:167], v[144:159]
	v_add_u32_e32 v181, s68, v213
	ds_read_b128 v[116:119], v181
	v_exp_f32_e32 v228, v120
	v_exp_f32_e32 v229, v121
	v_exp_f32_e32 v230, v122
	v_exp_f32_e32 v231, v123
	v_cvt_pk_bf16_f32 v112, v220, v221
	v_cvt_pk_bf16_f32 v113, v222, v223
	v_cvt_pk_bf16_f32 v114, v224, v225
	v_cvt_pk_bf16_f32 v115, v226, v227
	v_pk_add_f32 v[122:123], v[226:227], v[222:223]
	v_pk_add_f32 v[120:121], v[224:225], v[220:221]
	v_mfma_f32_32x32x16_bf16 v[128:143], v[182:185], v[164:167], v[128:143]
	ds_read_b128 v[176:179], v181 offset:8192
	v_exp_f32_e32 v124, v124
	v_exp_f32_e32 v125, v125
	v_exp_f32_e32 v126, v126
	v_exp_f32_e32 v127, v127
	s_waitcnt lgkmcnt(0)
	v_mfma_f32_32x32x16_bf16 v[144:159], v[186:189], v[168:171], v[144:159]
	v_add_f32_e64 v122, v230, v122
	v_add_f32_e64 v123, v231, v123
	v_add_f32_e64 v120, v228, v120
	v_add_f32_e64 v121, v229, v121
	v_exp_f32_e32 v182, v96
	v_exp_f32_e32 v183, v97
	v_exp_f32_e32 v184, v98
	v_exp_f32_e32 v185, v99
	v_cvt_pk_bf16_f32 v96, v228, v229
	v_cvt_pk_bf16_f32 v97, v230, v231
	v_cvt_pk_bf16_f32 v98, v124, v125
	v_cvt_pk_bf16_f32 v99, v126, v127
	v_pk_add_f32 v[122:123], v[126:127], v[122:123]
	v_pk_add_f32 v[120:121], v[124:125], v[120:121]
	v_mfma_f32_32x32x16_bf16 v[128:143], v[216:219], v[168:171], v[128:143]
	v_exp_f32_e32 v124, v100
	v_exp_f32_e32 v125, v101
	v_exp_f32_e32 v126, v102
	v_exp_f32_e32 v127, v103
	v_mfma_f32_32x32x16_bf16 v[144:159], v[116:119], v[172:175], v[144:159]
	v_exp_f32_e32 v186, v104
	v_exp_f32_e32 v187, v105
	v_exp_f32_e32 v188, v106
	v_exp_f32_e32 v189, v107
	v_pk_add_f32 v[106:107], v[184:185], v[122:123]
	v_pk_add_f32 v[104:105], v[182:183], v[120:121]
	v_cvt_pk_bf16_f32 v100, v182, v183
	v_cvt_pk_bf16_f32 v101, v184, v185
	v_cvt_pk_bf16_f32 v102, v124, v125
	v_cvt_pk_bf16_f32 v103, v126, v127
	v_pk_add_f32 v[118:119], v[126:127], v[106:107]
	v_pk_add_f32 v[116:117], v[124:125], v[104:105]
	v_mfma_f32_32x32x16_bf16 v[128:143], v[176:179], v[172:175], v[128:143]
	v_exp_f32_e32 v120, v108
	v_exp_f32_e32 v121, v109
	v_exp_f32_e32 v122, v110
	v_exp_f32_e32 v123, v111
	v_pk_add_f32 v[110:111], v[188:189], v[118:119]
	v_pk_add_f32 v[108:109], v[186:187], v[116:117]
	v_cvt_pk_bf16_f32 v104, v186, v187
	v_cvt_pk_bf16_f32 v105, v188, v189
	v_cvt_pk_bf16_f32 v106, v120, v121
	v_cvt_pk_bf16_f32 v107, v122, v123
	v_pk_add_f32 v[178:179], v[122:123], v[110:111]
	v_pk_add_f32 v[176:177], v[120:121], v[108:109]
	s_waitcnt vmcnt(4) lgkmcnt(0)
	s_barrier
	s_add_u32 s70, s98, 0x18000
	s_addc_u32 s71, s99, 0
	s_add_i32 s68, s68, s57
	s_mov_b32 m0, s68
	s_nop 0
	global_load_lds_dwordx4 v198, s[70:71]
	s_add_i32 m0, s68, 0x400
	s_nop 0
	global_load_lds_dwordx4 v194, s[70:71]
	s_add_u32 s2, s100, 0x80
	s_addc_u32 s3, s101, 0
	s_add_i32 s49, s58, s49
	s_add_i32 m0, s49, 0xc000
	s_nop 0
	global_load_lds_dwordx4 v196, s[2:3]
	s_add_i32 m0, s49, 0xc400
	s_nop 0
	global_load_lds_dwordx4 v192, s[2:3]
	s_add_i32 s2, s46, 0xffff4000
	s_add_i32 s3, s48, 1
	s_cmp_lg_u32 s48, 2
	s_cselect_b32 s48, s3, 0
	s_and_b32 s2, s2, 0xc000
	s_add_i32 s2, s2, 0
	s_lshl_b32 s3, s48, 14
	v_add_u32_e32 v124, s2, v206
	ds_read_b128 v[108:111], v124 offset:49152
	ds_read_b128 v[116:119], v124 offset:53248
	ds_read_b128 v[120:123], v124 offset:57344
	ds_read_b128 v[124:127], v124 offset:61440
	s_waitcnt lgkmcnt(0)
	v_mfma_f32_32x32x16_bf16 v[80:95], v[108:111], v[112:115], v[80:95]
	v_xad_u32 v182, v206, 32, s2
	ds_read_b128 v[108:111], v182 offset:49152
	s_add_i32 s3, s3, 0
	v_mfma_f32_32x32x16_bf16 v[64:79], v[116:119], v[112:115], v[64:79]
	ds_read_b128 v[116:119], v182 offset:53248
	v_mfma_f32_32x32x16_bf16 v[16:31], v[120:123], v[112:115], v[16:31]
	ds_read_b128 v[120:123], v182 offset:57344
	v_mfma_f32_32x32x16_bf16 v[0:15], v[124:127], v[112:115], v[0:15]
	ds_read_b128 v[112:115], v182 offset:61440
	s_waitcnt lgkmcnt(0)
	v_mfma_f32_32x32x16_bf16 v[80:95], v[108:111], v[96:99], v[80:95]
	v_xad_u32 v124, v206, 64, s2
	ds_read_b128 v[108:111], v124 offset:49152
	v_mfma_f32_32x32x16_bf16 v[64:79], v[116:119], v[96:99], v[64:79]
	ds_read_b128 v[116:119], v124 offset:53248
	v_mfma_f32_32x32x16_bf16 v[16:31], v[120:123], v[96:99], v[16:31]
	ds_read_b128 v[120:123], v124 offset:57344
	v_mfma_f32_32x32x16_bf16 v[0:15], v[112:115], v[96:99], v[0:15]
	ds_read_b128 v[96:99], v124 offset:61440
	s_waitcnt lgkmcnt(0)
	v_mfma_f32_32x32x16_bf16 v[80:95], v[108:111], v[100:103], v[80:95]
	v_add_u32_e32 v124, s2, v209
	ds_read_b128 v[108:111], v124 offset:49152
	v_mfma_f32_32x32x16_bf16 v[64:79], v[116:119], v[100:103], v[64:79]
	ds_read_b128 v[112:115], v124 offset:53248
	v_mfma_f32_32x32x16_bf16 v[16:31], v[120:123], v[100:103], v[16:31]
	ds_read_b128 v[116:119], v124 offset:57344
	v_mfma_f32_32x32x16_bf16 v[0:15], v[96:99], v[100:103], v[0:15]
	ds_read_b128 v[120:123], v124 offset:61440
	s_waitcnt lgkmcnt(0)
	v_mfma_f32_32x32x16_bf16 v[80:95], v[108:111], v[104:107], v[80:95]
	v_add_u32_e32 v100, s3, v205
	ds_read_b128 v[96:99], v100
	v_mfma_f32_32x32x16_bf16 v[64:79], v[112:115], v[104:107], v[64:79]
	ds_read_b128 v[100:103], v100 offset:8192
	v_mfma_f32_32x32x16_bf16 v[16:31], v[116:119], v[104:107], v[16:31]
	v_xad_u32 v108, v205, 32, s3
	ds_read_b128 v[182:185], v108
	v_mfma_f32_32x32x16_bf16 v[0:15], v[120:123], v[104:107], v[0:15]
	ds_read_b128 v[186:189], v108 offset:8192
	s_waitcnt lgkmcnt(0)
	v_mfma_f32_32x32x16_bf16 v[112:127], v[96:99], v[160:163], 0
	v_xad_u32 v104, v205, 64, s3
	ds_read_b128 v[216:219], v104
	v_exp_f32_e32 v224, v144
	v_exp_f32_e32 v225, v145
	v_exp_f32_e32 v226, v146
	v_exp_f32_e32 v227, v147
	ds_read_b128 v[220:223], v104 offset:8192
	v_mfma_f32_32x32x16_bf16 v[96:111], v[100:103], v[160:163], 0
	v_exp_f32_e32 v228, v148
	v_exp_f32_e32 v229, v149
	v_exp_f32_e32 v230, v150
	v_exp_f32_e32 v231, v151
	v_mfma_f32_32x32x16_bf16 v[112:127], v[182:185], v[164:167], v[112:127]
	v_add_u32_e32 v181, s3, v213
	ds_read_b128 v[148:151], v181
	v_exp_f32_e32 v232, v152
	v_exp_f32_e32 v233, v153
	v_exp_f32_e32 v234, v154
	v_exp_f32_e32 v235, v155
	v_cvt_pk_bf16_f32 v144, v224, v225
	v_cvt_pk_bf16_f32 v145, v226, v227
	v_cvt_pk_bf16_f32 v146, v228, v229
	v_cvt_pk_bf16_f32 v147, v230, v231
	v_pk_add_f32 v[154:155], v[230:231], v[226:227]
	v_pk_add_f32 v[152:153], v[228:229], v[224:225]
	v_mfma_f32_32x32x16_bf16 v[96:111], v[186:189], v[164:167], v[96:111]
	ds_read_b128 v[182:185], v181 offset:8192
	v_exp_f32_e32 v156, v156
	v_exp_f32_e32 v157, v157
	v_exp_f32_e32 v158, v158
	v_exp_f32_e32 v159, v159
	s_waitcnt lgkmcnt(0)
	v_mfma_f32_32x32x16_bf16 v[112:127], v[216:219], v[168:171], v[112:127]
	v_add_f32_e64 v154, v234, v154
	v_add_f32_e64 v155, v235, v155
	v_add_f32_e64 v152, v232, v152
	v_add_f32_e64 v153, v233, v153
	v_exp_f32_e32 v186, v128
	v_exp_f32_e32 v187, v129
	v_exp_f32_e32 v188, v130
	v_exp_f32_e32 v189, v131
	v_cvt_pk_bf16_f32 v128, v232, v233
	v_cvt_pk_bf16_f32 v129, v234, v235
	v_cvt_pk_bf16_f32 v130, v156, v157
	v_cvt_pk_bf16_f32 v131, v158, v159
	v_pk_add_f32 v[154:155], v[158:159], v[154:155]
	v_pk_add_f32 v[152:153], v[156:157], v[152:153]
	v_mfma_f32_32x32x16_bf16 v[96:111], v[220:223], v[168:171], v[96:111]
	v_exp_f32_e32 v156, v132
	v_exp_f32_e32 v157, v133
	v_exp_f32_e32 v158, v134
	v_exp_f32_e32 v159, v135
	v_mfma_f32_32x32x16_bf16 v[112:127], v[148:151], v[172:175], v[112:127]
	v_exp_f32_e32 v216, v136
	v_exp_f32_e32 v217, v137
	v_exp_f32_e32 v218, v138
	v_exp_f32_e32 v219, v139
	v_pk_add_f32 v[138:139], v[188:189], v[154:155]
	v_pk_add_f32 v[136:137], v[186:187], v[152:153]
	v_cvt_pk_bf16_f32 v132, v186, v187
	v_cvt_pk_bf16_f32 v133, v188, v189
	v_cvt_pk_bf16_f32 v134, v156, v157
	v_cvt_pk_bf16_f32 v135, v158, v159
	v_pk_add_f32 v[150:151], v[158:159], v[138:139]
	v_pk_add_f32 v[148:149], v[156:157], v[136:137]
	v_mfma_f32_32x32x16_bf16 v[96:111], v[182:185], v[172:175], v[96:111]
	v_exp_f32_e32 v152, v140
	v_exp_f32_e32 v153, v141
	v_exp_f32_e32 v154, v142
	v_exp_f32_e32 v155, v143
	v_pk_add_f32 v[142:143], v[218:219], v[150:151]
	v_pk_add_f32 v[140:141], v[216:217], v[148:149]
	v_cvt_pk_bf16_f32 v136, v216, v217
	v_cvt_pk_bf16_f32 v137, v218, v219
	v_cvt_pk_bf16_f32 v138, v152, v153
	v_cvt_pk_bf16_f32 v139, v154, v155
	v_pk_add_f32 v[142:143], v[154:155], v[142:143]
	v_pk_add_f32 v[140:141], v[152:153], v[140:141]
	s_waitcnt vmcnt(4) lgkmcnt(0)
	v_add_f32_e32 v148, v176, v177
	v_add_f32_e32 v149, v178, v179
	v_add_f32_e32 v148, v148, v149
	v_add_f32_e32 v140, v140, v141
	v_add_f32_e32 v141, v142, v143
	s_barrier
	v_add_f32_e32 v148, v180, v148
	v_add_f32_e32 v140, v140, v141
	v_add_f32_e32 v180, v148, v140
	s_add_i32 s47, s47, 2
	s_addk_i32 s41, 0x80
	s_add_i32 s46, s46, 0x8000
	s_add_u32 s98, s98, 0x30000
	s_addc_u32 s99, s99, 0
	s_add_u32 s100, s100, 0x100
	s_addc_u32 s101, s101, 0
	s_cmp_lt_u32 s47, 60
	s_cbranch_scc1 .Lst1_loop
	s_branch .LBB0_914

; #define LAS __attribute__((address_space(3)))
; __global__ void __launch_bounds__(512, 2) mk_fwd(Args A) {
;     extern __shared__ __attribute__((aligned(16))) unsigned char lds_raw[];
;     LAS unsigned char* lds = (LAS unsigned char*)lds_raw;
;     const int tid = threadIdx.x, lane = tid & 63, wave = __builtin_amdgcn_readfirstlane(tid >> 6);
	.amdhsa_kernel _Z6mk_fwd4Args
		.amdhsa_group_segment_fixed_size 0
		.amdhsa_private_segment_fixed_size 0
		.amdhsa_kernarg_size 472
		.amdhsa_user_sgpr_count 2
		.amdhsa_user_sgpr_dispatch_ptr 0
		.amdhsa_user_sgpr_queue_ptr 0
		.amdhsa_user_sgpr_kernarg_segment_ptr 1
		.amdhsa_user_sgpr_dispatch_id 0
		.amdhsa_user_sgpr_kernarg_preload_length 0
		.amdhsa_user_sgpr_kernarg_preload_offset 0
		.amdhsa_user_sgpr_private_segment_size 0
		.amdhsa_uses_dynamic_stack 0
		.amdhsa_enable_private_segment 0
		.amdhsa_system_sgpr_workgroup_id_x 1
		.amdhsa_system_sgpr_workgroup_id_y 0
		.amdhsa_system_sgpr_workgroup_id_z 0
		.amdhsa_system_sgpr_workgroup_info 0
		.amdhsa_system_vgpr_workitem_id 2
		.amdhsa_next_free_vgpr 256
		.amdhsa_next_free_sgpr 102
		.amdhsa_accum_offset 256
		.amdhsa_reserve_vcc 1
		.amdhsa_float_round_mode_32 0
		.amdhsa_float_round_mode_16_64 0
		.amdhsa_float_denorm_mode_32 3
		.amdhsa_float_denorm_mode_16_64 3
		.amdhsa_dx10_clamp 1
		.amdhsa_ieee_mode 1
		.amdhsa_fp16_overflow 0
		.amdhsa_tg_split 0
		.amdhsa_exception_fp_ieee_invalid_op 0
		.amdhsa_exception_fp_denorm_src 0
		.amdhsa_exception_fp_ieee_div_zero 0
		.amdhsa_exception_fp_ieee_overflow 0
		.amdhsa_exception_fp_ieee_underflow 0
		.amdhsa_exception_fp_ieee_inexact 0
		.amdhsa_exception_int_div_zero 0
	.end_amdhsa_kernel

; __global__ void __launch_bounds__(512, 2) mk_fwd(Args A) {
amdhsa.kernels:
  - .agpr_count:     0
    .args:
      - .offset:         0
        .size:           216
        .value_kind:     by_value
      - .offset:         216
        .size:           4
        .value_kind:     hidden_block_count_x
      - .offset:         220
        .size:           4
        .value_kind:     hidden_block_count_y
      - .offset:         224
        .size:           4
        .value_kind:     hidden_block_count_z
      - .offset:         228
        .size:           2
        .value_kind:     hidden_group_size_x
      - .offset:         230
        .size:           2
        .value_kind:     hidden_group_size_y
      - .offset:         232
        .size:           2
        .value_kind:     hidden_group_size_z
      - .offset:         234
        .size:           2
        .value_kind:     hidden_remainder_x
      - .offset:         236
        .size:           2
        .value_kind:     hidden_remainder_y
      - .offset:         238
        .size:           2
        .value_kind:     hidden_remainder_z
      - .offset:         256
        .size:           8
        .value_kind:     hidden_global_offset_x
      - .offset:         264
        .size:           8
        .value_kind:     hidden_global_offset_y
      - .offset:         272
        .size:           8
        .value_kind:     hidden_global_offset_z
      - .offset:         280
        .size:           2
        .value_kind:     hidden_grid_dims
      - .offset:         304
        .size:           8
        .value_kind:     hidden_multigrid_sync_arg
      - .offset:         336
        .size:           4
        .value_kind:     hidden_dynamic_lds_size
    .group_segment_fixed_size: 0
    .kernarg_segment_align: 8
    .kernarg_segment_size: 472
    .language:       OpenCL C
    .language_version:
      - 2
      - 0
    .max_flat_workgroup_size: 512
    .name:           _Z6mk_fwd4Args
    .private_segment_fixed_size: 0
    .sgpr_count:     108
    .sgpr_spill_count: 107
    .symbol:         _Z6mk_fwd4Args.kd
    .uniform_work_group_size: 1
    .uses_dynamic_stack: false
    .vgpr_count:     256
    .vgpr_spill_count: 0
    .wavefront_size: 64
